# hgrn output unit epilogue: counted wait (vmcnt(30)) for the gate loads when the next unit's operands are in flight
# baseline (speedup 1.0000x reference)
.LBB0_729:
	s_or_b64 exec, exec, s[6:7]
	v_lshl_add_u32 v16, v211, 2, 0
	s_waitcnt lgkmcnt(0)
	s_barrier
	v_add_u32_e32 v18, 0x26000, v16
	s_waitcnt lgkmcnt(0)
	ds_read2st64_b32 v[16:17], v18 offset1:1
	ds_read2st64_b32 v[18:19], v18 offset0:2 offset1:3
	v_lshl_add_u32 v20, v212, 2, s47
	v_lshl_add_u32 v22, v20, 2, 0
	v_add_u32_e32 v23, 0x26400, v22
	s_waitcnt lgkmcnt(1)
	v_add_f32_e32 v16, v16, v17
	s_waitcnt lgkmcnt(0)
	v_add_f32_e32 v16, v16, v18
	v_add_f32_e32 v16, v16, v19
	v_fmamk_f32 v16, v16, 0x3c000000, v207
	v_mul_f32_e32 v17, 0x4b800000, v16
	v_cmp_gt_f32_e32 vcc, s68, v16
	s_mov_b64 s[6:7], s[0:1]
	s_nop 0
	v_cndmask_b32_e32 v16, v16, v17, vcc
	v_rsq_f32_e32 v21, v16
	ds_read_b128 v[16:19], v23
	v_mul_f32_e32 v20, 0x45800000, v21
	v_cndmask_b32_e32 v20, v21, v20, vcc
	v_pk_mul_f32 v[0:1], v[0:1], v[20:21] op_sel_hi:[1,0]
	v_pk_mul_f32 v[2:3], v[2:3], v[20:21] op_sel_hi:[1,0]
	s_waitcnt lgkmcnt(0)
	v_pk_mul_f32 v[0:1], v[16:17], v[0:1]
	v_pk_mul_f32 v[2:3], v[18:19], v[2:3]
	v_mad_u32_u24 v16, v211, s69, v22
	ds_write_b128 v16, v[0:3]
	ds_read_b128 v[0:3], v23 offset:32
	v_pk_mul_f32 v[4:5], v[4:5], v[20:21] op_sel_hi:[1,0]
	s_waitcnt lgkmcnt(0)
	v_pk_mul_f32 v[0:1], v[0:1], v[4:5]
	v_pk_mul_f32 v[4:5], v[6:7], v[20:21] op_sel_hi:[1,0]
	v_pk_mul_f32 v[6:7], v[10:11], v[20:21] op_sel_hi:[1,0]
	v_pk_mul_f32 v[2:3], v[2:3], v[4:5]
	ds_write_b128 v16, v[0:3] offset:32
	ds_read_b128 v[0:3], v23 offset:64
	v_pk_mul_f32 v[4:5], v[8:9], v[20:21] op_sel_hi:[1,0]
	s_cmp_lg_u64 s[40:41], 0
	s_cbranch_scc1 .Lgbv_pre
	s_waitcnt vmcnt(0)
	s_branch .Lgbv_join
.Lgbv_pre:
	s_waitcnt vmcnt(30)
.Lgbv_join:
	v_lshlrev_b32_e32 v8, 16, v84
	v_and_b32_e32 v9, 0xffff0000, v84
	s_nop 0
	v_and_b32_e32 v11, 0xffff0000, v80
	s_waitcnt lgkmcnt(0)
	v_pk_mul_f32 v[0:1], v[0:1], v[4:5]
	v_pk_mul_f32 v[2:3], v[2:3], v[6:7]
	ds_write_b128 v16, v[0:3] offset:64
	ds_read_b128 v[0:3], v23 offset:96
	v_pk_mul_f32 v[4:5], v[12:13], v[20:21] op_sel_hi:[1,0]
	v_pk_mul_f32 v[6:7], v[14:15], v[20:21] op_sel_hi:[1,0]
	s_waitcnt lgkmcnt(0)
	v_pk_mul_f32 v[0:1], v[0:1], v[4:5]
	v_pk_mul_f32 v[2:3], v[2:3], v[6:7]
	ds_write_b128 v16, v[0:3] offset:96
	v_lshlrev_b32_e32 v0, 2, v203
	v_mul_lo_u32 v1, v202, s69
	s_waitcnt lgkmcnt(0)
	s_barrier
	v_add3_u32 v10, 0, v0, v1
	ds_read_b128 v[0:3], v10
	ds_read_b128 v[4:7], v10 offset:16
	s_load_dwordx2 s[6:7], s[6:7], 0xa8
	s_waitcnt lgkmcnt(0)
	v_pk_mul_f32 v[0:1], v[0:1], v[8:9]
	v_lshlrev_b32_e32 v8, 16, v85
	v_and_b32_e32 v9, 0xffff0000, v85
	v_pk_mul_f32 v[2:3], v[2:3], v[8:9]
	v_cvt_pk_bf16_f32 v0, v0, v1
	v_cvt_pk_bf16_f32 v1, v2, v3
	v_lshlrev_b32_e32 v2, 16, v86
	v_and_b32_e32 v3, 0xffff0000, v86
	v_pk_mul_f32 v[2:3], v[4:5], v[2:3]
	v_lshlrev_b32_e32 v4, 16, v87
	v_and_b32_e32 v5, 0xffff0000, v87
	v_pk_mul_f32 v[4:5], v[6:7], v[4:5]
	v_cvt_pk_bf16_f32 v2, v2, v3
	v_cvt_pk_bf16_f32 v3, v4, v5
	v_lshlrev_b64 v[4:5], 11, v[204:205]
	v_lshl_add_u64 v[4:5], s[6:7], 0, v[4:5]
	v_lshl_add_u64 v[4:5], v[4:5], 0, s[42:43]
	v_lshl_add_u64 v[4:5], v[4:5], 0, v[200:201]
	v_add_co_u32_e32 v4, vcc, s45, v4
	s_mov_b64 s[6:7], s[0:1]
	s_nop 0
	v_addc_co_u32_e32 v5, vcc, 0, v5, vcc
	global_store_dwordx4 v[4:5], v[0:3], off offset:1024
	ds_read_b128 v[0:3], v10 offset:16896
	ds_read_b128 v[4:7], v10 offset:16912
	v_lshlrev_b32_e32 v10, 16, v80
	s_load_dwordx2 s[6:7], s[6:7], 0xa8
	s_waitcnt lgkmcnt(0)
	v_pk_mul_f32 v[0:1], v[0:1], v[10:11]
	v_lshlrev_b32_e32 v10, 16, v81
	v_and_b32_e32 v11, 0xffff0000, v81
	v_pk_mul_f32 v[2:3], v[2:3], v[10:11]
	v_cvt_pk_bf16_f32 v0, v0, v1
	v_cvt_pk_bf16_f32 v1, v2, v3
	v_lshlrev_b32_e32 v2, 16, v82
	v_and_b32_e32 v3, 0xffff0000, v82
	v_add_u32_e32 v8, 32, v202
	v_pk_mul_f32 v[2:3], v[4:5], v[2:3]
	v_lshlrev_b32_e32 v4, 16, v83
	v_and_b32_e32 v5, 0xffff0000, v83
	v_pk_mul_f32 v[4:5], v[6:7], v[4:5]
	v_ashrrev_i32_e32 v9, 31, v8
	v_cvt_pk_bf16_f32 v2, v2, v3
	v_cvt_pk_bf16_f32 v3, v4, v5
	v_lshl_add_u64 v[4:5], v[8:9], 0, s[10:11]
	v_lshlrev_b64 v[4:5], 11, v[4:5]
	v_lshl_add_u64 v[4:5], s[6:7], 0, v[4:5]
	v_lshl_add_u64 v[4:5], v[4:5], 0, s[42:43]
	v_lshl_add_u64 v[4:5], v[4:5], 0, v[200:201]
	v_add_co_u32_e32 v4, vcc, 0x5800000, v4
	s_nop 1
	v_addc_co_u32_e32 v5, vcc, 0, v5, vcc
	global_store_dwordx4 v[4:5], v[0:3], off offset:1024
	s_waitcnt vmcnt(2)
	s_andn2_b64 vcc, exec, s[40:41]
	s_cbranch_vccnz .LBB0_701
	s_branch .LBB0_701
